# experiment, not kept: last 1024 weight-transpose items popped dynamically at the attention phase exit instead of statically after the first unit (slower: items are as long as the idle window)
# baseline (speedup 1.0000x reference)
.LBB0_306:
	s_or_b64 exec, exec, s[0:1]
	v_readlane_b32 s0, v252, 1
	v_mov_b32_e32 v169, 0
	v_readlane_b32 s1, v252, 2
	v_mov_b32_e32 v5, 0x8000
	s_waitcnt lgkmcnt(0)
	s_barrier
	v_add_f32_e32 v2, v0, v2
	s_nop 0
	global_load_dword v4, v169, s[0:1] sc1
	v_add_f32_e32 v1, v1, v3
	global_load_dword v5, v5, s[62:63] offset:768 sc1
	s_mov_b32 s0, 0x3fb8aa3b
	v_lshrrev_b32_e32 v7, 4, v209
	v_lshlrev_b32_e32 v10, 4, v209
	v_mul_f32_e32 v13, 0x3fb8aa3b, v2
	v_lshrrev_b32_e32 v8, 5, v209
	v_lshrrev_b32_e32 v9, 3, v209
	v_mul_f32_e32 v14, 0x3fb8aa3b, v1
	v_and_b32_e32 v15, 51, v7
	v_and_b32_e32 v17, 0xf0, v10
	v_mul_u32_u24_e32 v7, 0x1400, v7
	v_fma_f32 v20, v2, s0, -v13
	v_rndne_f32_e32 v21, v13
	v_and_b32_e32 v8, 4, v8
	v_and_b32_e32 v16, 8, v9
	v_fma_f32 v22, v1, s0, -v14
	v_rndne_f32_e32 v23, v14
	v_or_b32_e32 v170, v17, v7
	v_fmac_f32_e32 v20, 0x32a5705f, v2
	v_sub_f32_e32 v7, v13, v21
	v_or3_b32 v8, v15, v8, v16
	v_fmac_f32_e32 v22, 0x32a5705f, v1
	v_sub_f32_e32 v14, v14, v23
	v_add_f32_e32 v7, v7, v20
	v_cvt_i32_f32_e32 v13, v21
	v_mul_u32_u24_e32 v8, 0x110, v8
	v_add_f32_e32 v14, v14, v22
	v_exp_f32_e32 v7, v7
	v_cvt_i32_f32_e32 v15, v23
	v_add3_u32 v212, 0, v8, v17
	v_exp_f32_e32 v8, v14
	s_mov_b32 s1, 0xc2ce8ed0
	v_ldexp_f32 v7, v7, v13
	v_cmp_ngt_f32_e32 vcc, s1, v2
	s_mov_b32 s33, 0x42b17218
	v_ldexp_f32 v8, v8, v15
	v_cndmask_b32_e32 v7, 0, v7, vcc
	v_cmp_ngt_f32_e32 vcc, s1, v1
	v_mov_b32_e32 v3, 0x7f800000
	s_mov_b32 s38, 0xf800000
	v_cndmask_b32_e32 v8, 0, v8, vcc
	v_cmp_nlt_f32_e32 vcc, s33, v2
	s_add_u32 s4, s62, 0xc00000
	s_addc_u32 s5, s63, 0
	v_cndmask_b32_e32 v2, v3, v7, vcc
	v_cmp_nlt_f32_e32 vcc, s33, v1
	s_add_u32 s6, s62, 0xd00000
	s_addc_u32 s7, s63, 0
	v_cndmask_b32_e32 v1, v3, v8, vcc
	v_sub_f32_e32 v1, v2, v1
	v_add_f32_e32 v172, 0x3eb60549, v1
	s_add_u32 s34, s62, 0xe00000
	s_addc_u32 s35, s63, 0
	s_add_u32 s26, s62, 0x1000000
	s_addc_u32 s27, s63, 0
	v_mov_b32_e32 v6, 0x260
	s_add_u32 s24, s62, 0x1b00000
	s_addc_u32 s25, s63, 0
	s_add_u32 s36, s62, 0x1c900000
	s_addc_u32 s37, s63, 0
	v_mul_u32_u24_e32 v11, 0x110, v167
	v_lshlrev_b32_e32 v12, 4, v166
	s_add_u32 s40, s62, 0x8000
	s_addc_u32 s41, s63, 0
	v_add3_u32 v214, 0, v11, v12
	v_lshlrev_b32_e32 v0, 3, v166
	s_add_i32 s66, s64, 0xa00
	v_lshlrev_b32_e32 v168, 2, v167
	v_and_b32_e32 v18, 0x70, v10
	v_mul_u32_u24_e32 v19, 0x10080, v9
	v_mul_u32_u24_e32 v9, 0x90, v9
	v_lshl_add_u64 v[194:195], s[30:31], 0, v[168:169]
	s_movk_i32 s30, 0xff80
	s_mov_b32 s44, 0xfffb0000
	s_movk_i32 s13, 0x1400
	v_mov_b32_e32 v171, v169
	v_lshl_add_u32 v216, v129, 2, 0
	v_lshl_add_u64 v[174:175], s[56:57], 0, v[168:169]
	s_movk_i32 s67, 0x84
	v_or_b32_e32 v219, 8, v177
	s_waitcnt vmcnt(0)
	v_mul_f32_e32 v2, v4, v5
	v_mul_f32_e32 v3, 0x4f800000, v2
	v_cmp_gt_f32_e32 vcc, s38, v2
	v_or_b32_e32 v220, 16, v177
	v_or_b32_e32 v221, 24, v177
	v_cndmask_b32_e32 v2, v2, v3, vcc
	v_sqrt_f32_e32 v3, v2
	v_lshl_add_u64 v[180:181], s[54:55], 0, v[168:169]
	v_lshl_add_u64 v[184:185], s[52:53], 0, v[168:169]
	v_lshl_add_u64 v[186:187], s[48:49], 0, v[168:169]
	v_add_u32_e32 v1, -1, v3
	v_add_u32_e32 v4, 1, v3
	v_fma_f32 v5, -v1, v3, v2
	v_fma_f32 v7, -v4, v3, v2
	v_cmp_ge_f32_e64 s[0:1], 0, v5
	v_mov_b32_e32 v5, v169
	v_lshl_add_u64 v[190:191], s[46:47], 0, v[168:169]
	v_cndmask_b32_e64 v1, v3, v1, s[0:1]
	v_cmp_lt_f32_e64 s[0:1], 0, v7
	v_mov_b32_e32 v173, v172
	v_mov_b32_e32 v165, v166
	v_cndmask_b32_e64 v1, v1, v4, s[0:1]
	v_mul_f32_e32 v3, 0x37800000, v1
	v_cndmask_b32_e32 v1, v1, v3, vcc
	v_cmp_class_f32_e32 vcc, v2, v6
	s_add_i32 s0, 0, 0x12000
	v_add_u32_e32 v217, s0, v12
	v_cndmask_b32_e32 v1, v1, v2, vcc
	v_add_f32_e32 v1, v1, v1
	v_mul_f32_e32 v1, 0x3f828f5c, v1
	v_sub_f32_e32 v253, 0, v1
	v_mov_b32_e32 v254, 0x42400000
	v_cmp_lt_f32_e64 s[98:99], v1, v254
	s_nop 1
	v_cndmask_b32_e64 v253, 0, v253, s[98:99]
	s_getreg_b32 s100, hwreg(HW_REG_XCC_ID, 0, 4)
	s_and_b32 s100, s100, 7
	s_mov_b32 s101, 0
	s_mov_b32 s32, 0
	v_fmaak_f32 v213, 2.0, v1, 0x43160000
	v_mov_b32_e32 v254, 0x42fe0000
	v_cndmask_b32_e64 v213, v213, v254, s[98:99]
	v_lshlrev_b32_e32 v1, 7, v167
	v_sub_u32_e32 v215, v214, v1
	s_mul_i32 s0, s78, 0x2200
	v_and_b32_e32 v1, 56, v200
	s_add_i32 s0, s0, 0
	v_mul_u32_u24_e32 v3, 0x84, v1
	v_lshlrev_b32_e32 v4, 1, v1
	v_lshlrev_b32_e32 v1, 2, v177
	v_add3_u32 v218, s0, v3, v1
	v_add_u32_e32 v1, 0, v10
	v_lshlrev_b32_e32 v2, 2, v166
	s_cmpk_lt_i32 s64, 0x1480
	v_add_u32_e32 v176, s0, v168
	s_mov_b32 s0, 0x20000
	v_add_u32_e32 v224, 0xd000, v1
	v_sub_u32_e32 v1, v167, v0
	s_cselect_b64 s[42:43], -1, 0
	v_lshl_add_u64 v[178:179], s[24:25], 0, v[4:5]
	v_lshl_add_u64 v[182:183], s[26:27], 0, v[4:5]
	v_lshl_add_u64 v[188:189], s[34:35], 0, v[4:5]
	v_lshl_add_u64 v[192:193], s[6:7], 0, v[4:5]
	v_lshl_add_u64 v[196:197], s[4:5], 0, v[4:5]
	v_cmp_gt_i32_e64 s[0:1], s0, v164
	s_lshl_b32 s68, s14, 9
	v_add3_u32 v222, 0, v9, v18
	v_add_u32_e32 v223, 0xfffffe00, v209
	v_or_b32_e32 v198, v19, v18
	v_mov_b32_e32 v199, v169
	v_add_u32_e32 v225, 0xffffff80, v1
	v_lshl_add_u32 v226, s2, 12, v200
	s_lshl_b32 s69, s14, 12
	s_mov_b64 s[52:53], 0
	s_add_i32 s70, 0, 0x12400
	v_lshlrev_b32_e32 v200, 1, v0
	s_movk_i32 s71, 0x27f
	s_mov_b32 s72, 0xc2fc0000
	s_mov_b32 s73, 0xff61b1e6
	s_mov_b32 s74, 0x40c00000
	s_mov_b32 s31, -1
	s_mov_b32 s45, -1
	v_lshlrev_b32_e32 v202, 1, v2
	v_mov_b32_e32 v227, 0x358637bd
	s_movk_i32 s75, 0x2c00
	s_mov_b64 s[46:47], 0x1000
	s_mov_b32 s76, 0x6800000
	s_mov_b32 s77, 0x1a900000
	s_mov_b32 s78, 0x6801000
	s_mov_b32 s79, 0x6802000
	s_mov_b32 s80, 0x6803000
	s_mov_b32 s81, 0x6804000
	s_mov_b64 s[48:49], 0x5000
	s_mov_b32 s82, 0x1ffff
	v_mov_b32_e32 v240, v169
	v_mov_b32_e32 v241, v169
	v_mov_b32_e32 v242, v169
	v_mov_b32_e32 v243, v169
	v_mov_b32_e32 v228, 0x42800000
	v_mov_b32_e32 v229, 0x7149f2ca
	s_branch .LBB0_309

.LBB0_360:
	s_add_i32 s56, s56, s12
	s_cmp_eq_u32 s32, 1
	s_cbranch_scc1 .Ldyn_loop
	s_cmpk_gt_i32 s56, 0x1a7f
	s_cbranch_scc1 .LBB0_353

.LBB0_393:
	s_mov_b32 s32, 1
.Ldyn_loop:
	v_mov_b32_e32 v0, 0x1e0
	v_mov_b32_e32 v1, 1
	s_mov_b64 s[54:55], exec
	s_mov_b64 exec, 1
	global_atomic_add v1, v0, v1, s[40:41] sc0
	s_waitcnt vmcnt(0)
	s_mov_b64 exec, s[54:55]
	s_nop 1
	v_readfirstlane_b32 s56, v1
	s_nop 1
	s_add_i32 s56, s56, 0x1a80
	s_cmpk_gt_i32 s56, 0x1e7f
	s_cbranch_scc1 .Ldyn_done
	s_branch .LBB0_361
.Ldyn_done:
	s_mov_b32 s32, 0
	s_waitcnt vmcnt(0)
	s_barrier
	s_and_saveexec_b64 s[0:1], s[10:11]
	v_readlane_b32 s68, v252, 3
	v_readlane_b32 s74, v252, 9
	v_readlane_b32 s75, v252, 10
	v_readlane_b32 s69, v252, 4
	v_readlane_b32 s70, v252, 5
	v_readlane_b32 s71, v252, 6
	v_readlane_b32 s72, v252, 7
	v_readlane_b32 s73, v252, 8
	s_cbranch_execz .LBB0_445
	s_add_i32 s12, 0, 0x23fc0
	v_mov_b32_e32 v0, s12
	s_waitcnt vmcnt(0) expcnt(0) lgkmcnt(0)
	ds_read_b32 v2, v0
	s_add_i32 s12, 0, 0x23fc4
	v_mov_b32_e32 v0, s12
	ds_read_b32 v0, v0
	s_waitcnt lgkmcnt(1)
	v_cmp_ne_u32_e32 vcc, 0, v2
	s_cbranch_vccnz .LBB0_409
	v_readlane_b32 s12, v252, 0
	s_mul_i32 s33, s15, s12
	s_add_u32 s12, s62, 0x1000
	s_addc_u32 s13, s63, 0
	s_add_u32 s28, s62, 0x1100
	s_addc_u32 s29, s63, 0
	s_add_u32 s30, s62, 0x1200
	s_addc_u32 s31, s63, 0
	s_add_u32 s38, s62, 0x1300
	s_mul_i32 s33, s33, s14
	s_addc_u32 s39, s63, 0
	s_mov_b32 s46, 1
	v_mov_b32_e32 v16, 0
	s_branch .LBB0_397
